# adds: last-layer post-norm rows: RSQ load issued before the next row prefetch, counted vmcnt(32) instead of a full drain per row
# speedup vs baseline: 1.0014x; 1.0014x over previous
; #define GAS __attribute__((address_space(1)))
; __device__ __forceinline__ float bf_lo(unsigned w) { return __uint_as_float(w << 16); }
; __device__ __forceinline__ float bf_hi(unsigned w) { return __uint_as_float(w & 0xffff0000u); }
; __device__ __forceinline__ void pnl_load(const Frame& F, int m, int lane, u32x2 (&xw)[16], u32x2 (&ov)[16]) {
;     const GAS u32x2* x1row = (const GAS u32x2*)(F.P + (size_t)m * INW + 18432) + lane; const GAS u32x2* orow = (const GAS u32x2*)(F.X + (size_t)m * DM) + lane;
; #pragma unroll
;     for (int j = 0; j < 16; ++j) { xw[j] = x1row[64 * j]; ov[j] = orow[64 * j]; }
; }
; __device__ __forceinline__ void pnl_finish(const Frame& F, int m, int lane, const u32x2 (&xw)[16], const u32x2 (&ov)[16], const f32x4 (&gv)[16]) {
;     GAS f32x4* yo = (GAS f32x4*)(F.out + (size_t)m * DM) + lane;
;     const float ss = wave_sum(F.RSQ[(size_t)m * 64 + lane], lane);
;     const float r = 1.0f / sqrtf(ss * (1.0f / DM) + RMS_EPS);
; #pragma unroll
;     for (int j = 0; j < 16; ++j) { const u32x2 x = xw[j], ow = ov[j]; const f32x4 g = gv[j];
;         f32x4 y; y.x = bf_lo(x.x) + bf_lo(ow.x) * r * g.x; y.y = bf_hi(x.x) + bf_hi(ow.x) * r * g.y; y.z = bf_lo(x.y) + bf_lo(ow.y) * r * g.z; y.w = bf_hi(x.y) + bf_hi(ow.y) * r * g.w;
;         yo[64 * j] = y; }
; }
; __device__ __forceinline__ void post_norm_phase(Frame& F, int l) {
;     const int gw = F.vcu * NWAVES + F.wave, NGW = F.G * NWAVES, lane = F.lane;
;     const float* pg = F.post_norm + l * DM; const float* npre = (l + 1 < DEPTH) ? F.pre_norm + (l + 1) * DM : nullptr;
;     if (l > 0 && !npre) {
;         f32x4 gv[16]; u32x2 xa[16], oa[16], xb[16], ob[16];
; #pragma unroll
;         for (int j = 0; j < 16; ++j) gv[j] = ((const GAS f32x4*)pg)[lane + 64 * j];
;         int m = gw; if (m >= T) return;
;         pnl_load(F, m, lane, xa, oa);
.LBB0_1018:
	s_andn2_b64 vcc, exec, s[10:11]
	s_cbranch_vccnz .LBB0_1029
	s_cmpk_gt_i32 s88, 0x5fff
	s_cbranch_scc1 .LBB0_1029
	v_ashrrev_i32_e32 v139, 31, v138
	v_lshl_add_u64 v[66:67], v[138:139], 4, v[142:143]
	v_add_co_u32_e32 v18, vcc, 0x3000, v66
	s_mov_b64 s[4:5], 0x2e100000
	s_nop 0
	v_addc_co_u32_e32 v19, vcc, 0, v67, vcc
	v_lshl_add_u64 v[70:71], v[4:5], 0, s[4:5]
	v_add_co_u32_e32 v34, vcc, 0x2000, v66
	v_mad_i64_i32 v[74:75], s[4:5], s88, v126, v[140:141]
	v_lshlrev_b64 v[72:73], 3, v[138:139]
	v_addc_co_u32_e32 v35, vcc, 0, v67, vcc
	s_ashr_i32 s89, s88, 31
	v_lshl_add_u64 v[74:75], v[74:75], 0, v[72:73]
	s_mov_b64 s[4:5], 0x9000
	v_add_co_u32_e32 v50, vcc, 0x1000, v66
	v_lshl_add_u64 v[96:97], v[74:75], 0, s[4:5]
	s_lshl_b64 s[4:5], s[88:89], 13
	v_addc_co_u32_e32 v51, vcc, 0, v67, vcc
	v_lshl_add_u64 v[76:77], v[70:71], 0, s[4:5]
	s_mov_b32 s4, 0xa000
	v_add_co_u32_e32 v106, vcc, s4, v74
	v_lshl_add_u64 v[102:103], v[76:77], 0, v[72:73]
	s_nop 0
	v_addc_co_u32_e32 v107, vcc, 0, v75, vcc
	v_add_co_u32_e32 v136, vcc, s35, v102
	global_load_dwordx4 v[6:9], v[18:19], off offset:3072
	global_load_dwordx4 v[10:13], v[18:19], off offset:2048
	global_load_dwordx4 v[14:17], v[18:19], off offset:1024
	s_nop 0
	global_load_dwordx4 v[18:21], v[18:19], off
	v_addc_co_u32_e32 v137, vcc, 0, v103, vcc
	global_load_dwordx4 v[22:25], v[34:35], off offset:3072
	global_load_dwordx4 v[26:29], v[34:35], off offset:2048
	global_load_dwordx4 v[30:33], v[34:35], off offset:1024
	s_nop 0
	global_load_dwordx4 v[34:37], v[34:35], off
	s_nop 0
	global_load_dwordx4 v[38:41], v[50:51], off offset:3072
	global_load_dwordx4 v[42:45], v[50:51], off offset:2048
	global_load_dwordx4 v[46:49], v[50:51], off offset:1024
	s_nop 0
	global_load_dwordx4 v[50:53], v[50:51], off
	s_nop 0
	global_load_dwordx4 v[54:57], v[66:67], off offset:3072
	global_load_dwordx4 v[58:61], v[66:67], off offset:2048
	global_load_dwordx4 v[62:65], v[66:67], off offset:1024
	s_nop 0
	global_load_dwordx4 v[66:69], v[66:67], off
	s_nop 0
	global_load_dwordx2 v[74:75], v[96:97], off offset:512
	global_load_dwordx2 v[76:77], v[96:97], off offset:1024
	global_load_dwordx2 v[78:79], v[96:97], off offset:1536
	global_load_dwordx2 v[80:81], v[96:97], off offset:2048
	global_load_dwordx2 v[82:83], v[102:103], off offset:512
	global_load_dwordx2 v[84:85], v[102:103], off offset:1024
	global_load_dwordx2 v[86:87], v[102:103], off offset:1536
	global_load_dwordx2 v[88:89], v[102:103], off offset:2048
	global_load_dwordx2 v[90:91], v[102:103], off
	global_load_dwordx2 v[92:93], v[96:97], off offset:2560
	global_load_dwordx2 v[94:95], v[96:97], off offset:3072
	s_nop 0
	global_load_dwordx2 v[96:97], v[96:97], off offset:3584
	s_nop 0
	global_load_dwordx2 v[98:99], v[102:103], off offset:2560
	global_load_dwordx2 v[100:101], v[102:103], off offset:3072
	s_nop 0
	global_load_dwordx2 v[102:103], v[102:103], off offset:3584
	s_nop 0
	global_load_dwordx2 v[110:111], v[136:137], off
	global_load_dwordx2 v[104:105], v[106:107], off
	global_load_dwordx2 v[108:109], v[106:107], off offset:512
	global_load_dwordx2 v[112:113], v[106:107], off offset:1024
	global_load_dwordx2 v[114:115], v[106:107], off offset:1536
	global_load_dwordx2 v[116:117], v[136:137], off offset:512
	global_load_dwordx2 v[118:119], v[136:137], off offset:1024
	global_load_dwordx2 v[120:121], v[136:137], off offset:1536
	global_load_dwordx2 v[126:127], v[136:137], off offset:2048
	global_load_dwordx2 v[122:123], v[106:107], off offset:2048
	global_load_dwordx2 v[124:125], v[106:107], off offset:2560
	global_load_dwordx2 v[128:129], v[106:107], off offset:3072
	global_load_dwordx2 v[130:131], v[106:107], off offset:3584
	s_nop 0
	global_load_dwordx2 v[106:107], v[106:107], off offset:-4096
	s_nop 0
	global_load_dwordx2 v[132:133], v[136:137], off offset:2560
	global_load_dwordx2 v[134:135], v[136:137], off offset:3072
	s_nop 0
	global_load_dwordx2 v[136:137], v[136:137], off offset:3584
	v_lshlrev_b32_e32 v0, 2, v138
	v_lshl_add_u64 v[4:5], v[138:139], 2, v[4:5]
	s_mov_b64 s[4:5], 0x85100000
	v_mov_b32_e32 v224, 0xc000
	v_xor_b32_e32 v212, 4, v0
	v_xor_b32_e32 v213, 8, v0
	v_xor_b32_e32 v214, 16, v0
	v_xor_b32_e32 v215, 32, v0
	v_xor_b32_e32 v216, 64, v0
	v_xor_b32_e32 v217, 0x80, v0
	v_lshl_add_u64 v[4:5], v[4:5], 0, s[4:5]
	s_branch .LBB0_1023
.Lpn_a_last:
	s_waitcnt vmcnt(0)
	s_branch .Lpn_a_fin

; #define GAS __attribute__((address_space(1)))
; __device__ __forceinline__ float bf_lo(unsigned w) { return __uint_as_float(w << 16); }
; __device__ __forceinline__ float bf_hi(unsigned w) { return __uint_as_float(w & 0xffff0000u); }
; __device__ __forceinline__ void pnl_finish(const Frame& F, int m, int lane, const u32x2 (&xw)[16], const u32x2 (&ov)[16], const f32x4 (&gv)[16]) {
;     GAS f32x4* yo = (GAS f32x4*)(F.out + (size_t)m * DM) + lane;
;     const float ss = wave_sum(F.RSQ[(size_t)m * 64 + lane], lane);
;     const float r = 1.0f / sqrtf(ss * (1.0f / DM) + RMS_EPS);
; #pragma unroll
;     for (int j = 0; j < 16; ++j) { const u32x2 x = xw[j], ow = ov[j]; const f32x4 g = gv[j];
;         f32x4 y; y.x = bf_lo(x.x) + bf_lo(ow.x) * r * g.x; y.y = bf_hi(x.x) + bf_hi(ow.x) * r * g.y; y.z = bf_lo(x.y) + bf_lo(ow.y) * r * g.z; y.w = bf_hi(x.y) + bf_hi(ow.y) * r * g.w;
.LBB0_1021:
	s_waitcnt vmcnt(32)
.Lpn_b_fin:
	s_ashr_i32 s5, s4, 31
	s_lshl_b64 s[10:11], s[4:5], 14
	s_mov_b32 s4, 0xf800000
	v_and_b32_e32 v219, 0xffff0000, v175
	v_lshl_add_u64 v[206:207], v[2:3], 0, s[10:11]
	v_lshl_add_u64 v[206:207], v[138:139], 4, v[206:207]
	v_lshlrev_b32_e32 v222, 16, v181
	v_and_b32_e32 v223, 0xffff0000, v181
	s_waitcnt lgkmcnt(0)
	ds_bpermute_b32 v208, v212, v0
	s_waitcnt lgkmcnt(0)
	v_add_f32_e32 v0, v0, v208
	ds_bpermute_b32 v208, v213, v0
	s_waitcnt lgkmcnt(0)
	v_add_f32_e32 v0, v0, v208
	ds_bpermute_b32 v208, v214, v0
	s_waitcnt lgkmcnt(0)
	v_add_f32_e32 v0, v0, v208
	ds_bpermute_b32 v208, v215, v0
	s_waitcnt lgkmcnt(0)
	v_add_f32_e32 v0, v0, v208
	ds_bpermute_b32 v208, v216, v0
	s_waitcnt lgkmcnt(0)
	v_add_f32_e32 v0, v0, v208
	ds_bpermute_b32 v208, v217, v0
	s_waitcnt lgkmcnt(0)
	v_add_f32_e32 v0, v0, v208
	v_mov_b32_e32 v208, 0x358637bd
	v_fmamk_f32 v0, v0, 0x39800000, v208
	v_cmp_gt_f32_e32 vcc, s4, v0
	v_mul_f32_e32 v208, 0x4f800000, v0
	s_nop 0
	v_cndmask_b32_e32 v0, v0, v208, vcc
	v_sqrt_f32_e32 v208, v0
	s_nop 0
	v_add_u32_e32 v209, -1, v208
	v_fma_f32 v210, -v209, v208, v0
	v_cmp_ge_f32_e64 s[36:37], 0, v210
	v_add_u32_e32 v210, 1, v208
	s_nop 0
	v_cndmask_b32_e64 v209, v208, v209, s[36:37]
	v_fma_f32 v208, -v210, v208, v0
	v_cmp_lt_f32_e64 s[36:37], 0, v208
	s_nop 1
	v_cndmask_b32_e64 v208, v209, v210, s[36:37]
	v_mul_f32_e32 v209, 0x37800000, v208
	v_cndmask_b32_e32 v208, v208, v209, vcc
	v_mov_b32_e32 v209, 0x260
	v_cmp_class_f32_e32 vcc, v0, v209
	s_nop 1
	v_cndmask_b32_e32 v0, v208, v0, vcc
	v_div_scale_f32 v208, s[4:5], v0, v0, 1.0
	v_rcp_f32_e32 v209, v208
	s_movk_i32 s4, 0x2000
	v_fma_f32 v210, -v208, v209, 1.0
	v_fmac_f32_e32 v209, v210, v209
	v_div_scale_f32 v210, vcc, 1.0, v0, 1.0
	v_mul_f32_e32 v211, v210, v209
	v_fma_f32 v218, -v208, v211, v210
	v_fmac_f32_e32 v211, v218, v209
	v_fma_f32 v208, -v208, v211, v210
	v_div_fmas_f32 v208, v208, v209, v211
	v_div_fixup_f32 v0, v208, v0, 1.0
	v_lshlrev_b32_e32 v210, 16, v174
	v_and_b32_e32 v211, 0xffff0000, v174
	v_lshlrev_b32_e32 v208, 16, v156
	v_and_b32_e32 v209, 0xffff0000, v156
	v_pk_mul_f32 v[210:211], v[0:1], v[210:211] op_sel_hi:[0,1]
	v_lshlrev_b32_e32 v218, 16, v175
	v_pk_fma_f32 v[208:209], v[66:67], v[210:211], v[208:209]
	v_lshlrev_b32_e32 v210, 16, v157
	v_and_b32_e32 v211, 0xffff0000, v157
	v_pk_mul_f32 v[218:219], v[0:1], v[218:219] op_sel_hi:[0,1]
	v_pk_fma_f32 v[210:211], v[68:69], v[218:219], v[210:211]
	global_store_dwordx4 v[206:207], v[208:211], off
	v_lshlrev_b32_e32 v218, 16, v167
	v_and_b32_e32 v219, 0xffff0000, v167
	v_lshlrev_b32_e32 v210, 16, v166
	v_and_b32_e32 v211, 0xffff0000, v166
	v_lshlrev_b32_e32 v208, 16, v142
	v_and_b32_e32 v209, 0xffff0000, v142
	v_pk_mul_f32 v[210:211], v[0:1], v[210:211] op_sel_hi:[0,1]
	v_pk_fma_f32 v[208:209], v[62:63], v[210:211], v[208:209]
	v_lshlrev_b32_e32 v210, 16, v143
	v_and_b32_e32 v211, 0xffff0000, v143
	v_pk_mul_f32 v[218:219], v[0:1], v[218:219] op_sel_hi:[0,1]
	v_pk_fma_f32 v[210:211], v[64:65], v[218:219], v[210:211]
	global_store_dwordx4 v[206:207], v[208:211], off offset:1024
	v_lshlrev_b32_e32 v218, 16, v165
	v_and_b32_e32 v219, 0xffff0000, v165
	v_lshlrev_b32_e32 v210, 16, v164
	v_and_b32_e32 v211, 0xffff0000, v164
	v_lshlrev_b32_e32 v208, 16, v144
	v_and_b32_e32 v209, 0xffff0000, v144
	v_pk_mul_f32 v[210:211], v[0:1], v[210:211] op_sel_hi:[0,1]
	v_pk_fma_f32 v[208:209], v[58:59], v[210:211], v[208:209]
	v_lshlrev_b32_e32 v210, 16, v145
	v_and_b32_e32 v211, 0xffff0000, v145
	v_pk_mul_f32 v[218:219], v[0:1], v[218:219] op_sel_hi:[0,1]
	v_pk_fma_f32 v[210:211], v[60:61], v[218:219], v[210:211]
	global_store_dwordx4 v[206:207], v[208:211], off offset:2048
	v_lshlrev_b32_e32 v218, 16, v163
	v_and_b32_e32 v219, 0xffff0000, v163
	v_lshlrev_b32_e32 v210, 16, v162
	v_and_b32_e32 v211, 0xffff0000, v162
	v_lshlrev_b32_e32 v208, 16, v146
	v_and_b32_e32 v209, 0xffff0000, v146
	v_pk_mul_f32 v[210:211], v[0:1], v[210:211] op_sel_hi:[0,1]
	v_pk_fma_f32 v[208:209], v[54:55], v[210:211], v[208:209]
	v_lshlrev_b32_e32 v210, 16, v147
	v_and_b32_e32 v211, 0xffff0000, v147
	v_pk_mul_f32 v[218:219], v[0:1], v[218:219] op_sel_hi:[0,1]
	v_pk_fma_f32 v[210:211], v[56:57], v[218:219], v[210:211]
	global_store_dwordx4 v[206:207], v[208:211], off offset:3072
	v_pk_mul_f32 v[222:223], v[0:1], v[222:223] op_sel_hi:[0,1]
	s_nop 0
	v_lshlrev_b32_e32 v210, 16, v160
	v_and_b32_e32 v211, 0xffff0000, v160
	v_lshlrev_b32_e32 v208, 16, v148
	v_and_b32_e32 v209, 0xffff0000, v148
	v_pk_mul_f32 v[210:211], v[0:1], v[210:211] op_sel_hi:[0,1]
	v_pk_fma_f32 v[218:219], v[50:51], v[210:211], v[208:209]
	v_lshlrev_b32_e32 v210, 16, v161
	v_and_b32_e32 v211, 0xffff0000, v161
	v_lshlrev_b32_e32 v208, 16, v149
	v_and_b32_e32 v209, 0xffff0000, v149
	v_pk_mul_f32 v[210:211], v[0:1], v[210:211] op_sel_hi:[0,1]
	v_pk_fma_f32 v[220:221], v[52:53], v[210:211], v[208:209]
	v_add_co_u32_e32 v210, vcc, s35, v206
	s_nop 1
	v_addc_co_u32_e32 v211, vcc, 0, v207, vcc
	v_add_co_u32_e32 v208, vcc, s4, v206
	s_movk_i32 s4, 0x3000
	s_nop 0
	v_addc_co_u32_e32 v209, vcc, 0, v207, vcc
	global_store_dwordx4 v[208:209], v[218:221], off offset:-4096
	s_nop 1
	v_lshlrev_b32_e32 v220, 16, v180
	v_and_b32_e32 v221, 0xffff0000, v180
	v_lshlrev_b32_e32 v218, 16, v150
	v_and_b32_e32 v219, 0xffff0000, v150
	v_pk_mul_f32 v[220:221], v[0:1], v[220:221] op_sel_hi:[0,1]
	v_pk_fma_f32 v[218:219], v[46:47], v[220:221], v[218:219]
	v_lshlrev_b32_e32 v220, 16, v151
	v_and_b32_e32 v221, 0xffff0000, v151
	v_pk_fma_f32 v[220:221], v[48:49], v[222:223], v[220:221]
	global_store_dwordx4 v[210:211], v[218:221], off offset:1024
	v_lshlrev_b32_e32 v222, 16, v179
; __device__ __forceinline__ float bf_lo(unsigned w) { return __uint_as_float(w << 16); }
; __device__ __forceinline__ float bf_hi(unsigned w) { return __uint_as_float(w & 0xffff0000u); }
; __device__ __forceinline__ void pnl_finish(const Frame& F, int m, int lane, const u32x2 (&xw)[16], const u32x2 (&ov)[16], const f32x4 (&gv)[16]) {
;     ...
;     for (int j = 0; j < 16; ++j) { const u32x2 x = xw[j], ow = ov[j]; const f32x4 g = gv[j];
;         f32x4 y; y.x = bf_lo(x.x) + bf_lo(ow.x) * r * g.x; y.y = bf_hi(x.x) + bf_hi(ow.x) * r * g.y; y.z = bf_lo(x.y) + bf_lo(ow.y) * r * g.z; y.w = bf_hi(x.y) + bf_hi(ow.y) * r * g.w;
;         yo[64 * j] = y; }
	v_and_b32_e32 v223, 0xffff0000, v179
	v_lshlrev_b32_e32 v220, 16, v178
	v_and_b32_e32 v221, 0xffff0000, v178
	v_lshlrev_b32_e32 v218, 16, v152
	v_and_b32_e32 v219, 0xffff0000, v152
	v_pk_mul_f32 v[220:221], v[0:1], v[220:221] op_sel_hi:[0,1]
	v_pk_fma_f32 v[218:219], v[42:43], v[220:221], v[218:219]
	v_lshlrev_b32_e32 v220, 16, v153
	v_and_b32_e32 v221, 0xffff0000, v153
	v_pk_mul_f32 v[222:223], v[0:1], v[222:223] op_sel_hi:[0,1]
	v_pk_fma_f32 v[220:221], v[44:45], v[222:223], v[220:221]
	global_store_dwordx4 v[210:211], v[218:221], off offset:2048
	v_lshlrev_b32_e32 v222, 16, v177
	v_and_b32_e32 v223, 0xffff0000, v177
	v_lshlrev_b32_e32 v220, 16, v176
	v_and_b32_e32 v221, 0xffff0000, v176
	v_lshlrev_b32_e32 v218, 16, v154
	v_and_b32_e32 v219, 0xffff0000, v154
	v_pk_mul_f32 v[220:221], v[0:1], v[220:221] op_sel_hi:[0,1]
	v_pk_fma_f32 v[218:219], v[38:39], v[220:221], v[218:219]
	v_lshlrev_b32_e32 v220, 16, v155
	v_and_b32_e32 v221, 0xffff0000, v155
	v_pk_mul_f32 v[222:223], v[0:1], v[222:223] op_sel_hi:[0,1]
	v_pk_fma_f32 v[220:221], v[40:41], v[222:223], v[220:221]
	global_store_dwordx4 v[210:211], v[218:221], off offset:3072
	v_lshlrev_b32_e32 v210, 16, v158
	v_and_b32_e32 v211, 0xffff0000, v158
	v_lshlrev_b32_e32 v218, 16, v196
	v_and_b32_e32 v219, 0xffff0000, v196
	v_pk_mul_f32 v[218:219], v[0:1], v[218:219] op_sel_hi:[0,1]
	v_lshlrev_b32_e32 v220, 16, v197
	v_and_b32_e32 v221, 0xffff0000, v197
	v_pk_fma_f32 v[218:219], v[34:35], v[218:219], v[210:211]
	v_lshlrev_b32_e32 v210, 16, v159
	v_and_b32_e32 v211, 0xffff0000, v159
	v_pk_mul_f32 v[220:221], v[0:1], v[220:221] op_sel_hi:[0,1]
	v_pk_fma_f32 v[220:221], v[36:37], v[220:221], v[210:211]
	global_store_dwordx4 v[208:209], v[218:221], off
	v_lshlrev_b32_e32 v210, 16, v168
	v_and_b32_e32 v211, 0xffff0000, v168
	v_lshlrev_b32_e32 v218, 16, v194
	v_and_b32_e32 v219, 0xffff0000, v194
	v_pk_mul_f32 v[218:219], v[0:1], v[218:219] op_sel_hi:[0,1]
	v_lshlrev_b32_e32 v220, 16, v195
	v_and_b32_e32 v221, 0xffff0000, v195
	v_pk_fma_f32 v[218:219], v[30:31], v[218:219], v[210:211]
	v_lshlrev_b32_e32 v210, 16, v169
	v_and_b32_e32 v211, 0xffff0000, v169
	v_pk_mul_f32 v[220:221], v[0:1], v[220:221] op_sel_hi:[0,1]
	v_pk_fma_f32 v[220:221], v[32:33], v[220:221], v[210:211]
	global_store_dwordx4 v[208:209], v[218:221], off offset:1024
	v_lshlrev_b32_e32 v210, 16, v170
	v_and_b32_e32 v211, 0xffff0000, v170
	v_lshlrev_b32_e32 v218, 16, v192
	v_and_b32_e32 v219, 0xffff0000, v192
	v_pk_mul_f32 v[218:219], v[0:1], v[218:219] op_sel_hi:[0,1]
	v_lshlrev_b32_e32 v220, 16, v193
	v_and_b32_e32 v221, 0xffff0000, v193
	v_pk_fma_f32 v[218:219], v[26:27], v[218:219], v[210:211]
	v_lshlrev_b32_e32 v210, 16, v171
	v_and_b32_e32 v211, 0xffff0000, v171
	v_pk_mul_f32 v[220:221], v[0:1], v[220:221] op_sel_hi:[0,1]
	v_pk_fma_f32 v[220:221], v[28:29], v[220:221], v[210:211]
	global_store_dwordx4 v[208:209], v[218:221], off offset:2048
	v_lshlrev_b32_e32 v210, 16, v172
	v_and_b32_e32 v211, 0xffff0000, v172
	v_lshlrev_b32_e32 v218, 16, v190
	v_and_b32_e32 v219, 0xffff0000, v190
	v_pk_mul_f32 v[218:219], v[0:1], v[218:219] op_sel_hi:[0,1]
	v_lshlrev_b32_e32 v220, 16, v191
	v_and_b32_e32 v221, 0xffff0000, v191
	v_pk_fma_f32 v[218:219], v[22:23], v[218:219], v[210:211]
	v_lshlrev_b32_e32 v210, 16, v173
	v_and_b32_e32 v211, 0xffff0000, v173
	v_pk_mul_f32 v[220:221], v[0:1], v[220:221] op_sel_hi:[0,1]
	v_pk_fma_f32 v[220:221], v[24:25], v[220:221], v[210:211]
	v_lshlrev_b32_e32 v210, 16, v204
	v_and_b32_e32 v211, 0xffff0000, v204
	global_store_dwordx4 v[208:209], v[218:221], off offset:3072
	v_lshlrev_b32_e32 v208, 16, v182
	v_and_b32_e32 v209, 0xffff0000, v182
	v_pk_mul_f32 v[210:211], v[0:1], v[210:211] op_sel_hi:[0,1]
	v_lshlrev_b32_e32 v218, 16, v205
	v_and_b32_e32 v219, 0xffff0000, v205
	v_pk_fma_f32 v[208:209], v[18:19], v[210:211], v[208:209]
	v_lshlrev_b32_e32 v210, 16, v183
	v_and_b32_e32 v211, 0xffff0000, v183
	v_pk_mul_f32 v[218:219], v[0:1], v[218:219] op_sel_hi:[0,1]
	v_pk_fma_f32 v[210:211], v[20:21], v[218:219], v[210:211]
	v_add_co_u32_e32 v218, vcc, s4, v206
	v_lshlrev_b32_e32 v206, 16, v184
	s_nop 0
	v_addc_co_u32_e32 v219, vcc, 0, v207, vcc
	global_store_dwordx4 v[218:219], v[208:211], off
	v_and_b32_e32 v207, 0xffff0000, v184
	s_nop 0
	v_lshlrev_b32_e32 v208, 16, v202
	v_and_b32_e32 v209, 0xffff0000, v202
	v_pk_mul_f32 v[208:209], v[0:1], v[208:209] op_sel_hi:[0,1]
	v_lshlrev_b32_e32 v210, 16, v203
	v_and_b32_e32 v211, 0xffff0000, v203
	v_pk_fma_f32 v[206:207], v[14:15], v[208:209], v[206:207]
	v_lshlrev_b32_e32 v208, 16, v185
	v_and_b32_e32 v209, 0xffff0000, v185
	v_pk_mul_f32 v[210:211], v[0:1], v[210:211] op_sel_hi:[0,1]
	v_pk_fma_f32 v[208:209], v[16:17], v[210:211], v[208:209]
	global_store_dwordx4 v[218:219], v[206:209], off offset:1024
	v_lshlrev_b32_e32 v210, 16, v201
	v_and_b32_e32 v211, 0xffff0000, v201
	v_lshlrev_b32_e32 v208, 16, v200
	v_and_b32_e32 v209, 0xffff0000, v200
	v_lshlrev_b32_e32 v206, 16, v186
	v_and_b32_e32 v207, 0xffff0000, v186
	v_pk_mul_f32 v[208:209], v[0:1], v[208:209] op_sel_hi:[0,1]
	v_pk_fma_f32 v[206:207], v[10:11], v[208:209], v[206:207]
	v_lshlrev_b32_e32 v208, 16, v187
	v_and_b32_e32 v209, 0xffff0000, v187
	v_pk_mul_f32 v[210:211], v[0:1], v[210:211] op_sel_hi:[0,1]
	v_pk_fma_f32 v[208:209], v[12:13], v[210:211], v[208:209]
	global_store_dwordx4 v[218:219], v[206:209], off offset:2048
	v_lshlrev_b32_e32 v210, 16, v199
	v_and_b32_e32 v211, 0xffff0000, v199
	v_lshlrev_b32_e32 v208, 16, v198
	v_and_b32_e32 v209, 0xffff0000, v198
	v_lshlrev_b32_e32 v206, 16, v188
	v_and_b32_e32 v207, 0xffff0000, v188
	v_pk_mul_f32 v[208:209], v[0:1], v[208:209] op_sel_hi:[0,1]
	v_pk_fma_f32 v[206:207], v[6:7], v[208:209], v[206:207]
	v_lshlrev_b32_e32 v208, 16, v189
	v_and_b32_e32 v209, 0xffff0000, v189
	v_pk_mul_f32 v[210:211], v[0:1], v[210:211] op_sel_hi:[0,1]
	v_pk_fma_f32 v[208:209], v[8:9], v[210:211], v[208:209]
	global_store_dwordx4 v[218:219], v[206:209], off offset:3072

; #define GAS __attribute__((address_space(1)))
; __device__ __forceinline__ void pnl_load(const Frame& F, int m, int lane, u32x2 (&xw)[16], u32x2 (&ov)[16]) {
;     const GAS u32x2* x1row = (const GAS u32x2*)(F.P + (size_t)m * INW + 18432) + lane; const GAS u32x2* orow = (const GAS u32x2*)(F.X + (size_t)m * DM) + lane;
; #pragma unroll
;     for (int j = 0; j < 16; ++j) { xw[j] = x1row[64 * j]; ov[j] = orow[64 * j]; }
; }
; __device__ __forceinline__ void pnl_finish(const Frame& F, int m, int lane, const u32x2 (&xw)[16], const u32x2 (&ov)[16], const f32x4 (&gv)[16]) {
;     GAS f32x4* yo = (GAS f32x4*)(F.out + (size_t)m * DM) + lane;
;     const float ss = wave_sum(F.RSQ[(size_t)m * 64 + lane], lane);
; __device__ __forceinline__ void post_norm_phase(Frame& F, int l) {
;     ...
;         for (;;) {
;             bool hn = m + NGW < T; if (hn) pnl_load(F, m + NGW, lane, xb, ob);
.LBB0_1023:
	s_ashr_i32 s89, s88, 31
	s_lshl_b64 s[8:9], s[88:89], 8
	v_lshl_add_u64 v[208:209], v[4:5], 0, s[8:9]
	global_load_dword v0, v[208:209], off
	s_add_i32 s4, s88, s96
	s_cmpk_lt_i32 s4, 0x6000
	s_cselect_b64 s[10:11], -1, 0
	s_cmpk_gt_i32 s4, 0x5fff
	s_cbranch_scc1 .Lpn_a_last
	v_mad_i64_i32 v[142:143], s[8:9], s4, v224, v[140:141]
	v_lshl_add_u64 v[158:159], v[142:143], 0, v[72:73]
	s_ashr_i32 s5, s4, 31
	s_mov_b64 s[8:9], 0x9000
	v_add_co_u32_e32 v156, vcc, 0x9000, v158
	v_lshl_add_u64 v[154:155], v[158:159], 0, s[8:9]
	s_lshl_b64 s[8:9], s[4:5], 13
	v_addc_co_u32_e32 v157, vcc, 0, v159, vcc
	s_mov_b32 s5, 0xa000
	v_lshl_add_u64 v[142:143], v[70:71], 0, s[8:9]
	v_add_co_u32_e32 v188, vcc, s5, v158
	v_lshl_add_u64 v[168:169], v[142:143], 0, v[72:73]
	s_nop 0
	v_addc_co_u32_e32 v189, vcc, 0, v159, vcc
	v_add_co_u32_e32 v198, vcc, s35, v168
	global_load_dwordx2 v[142:143], v[154:155], off offset:512
	global_load_dwordx2 v[144:145], v[154:155], off offset:1024
	global_load_dwordx2 v[146:147], v[154:155], off offset:1536
	global_load_dwordx2 v[148:149], v[154:155], off offset:2048
	global_load_dwordx2 v[166:167], v[168:169], off offset:512
	global_load_dwordx2 v[164:165], v[168:169], off offset:1024
	global_load_dwordx2 v[162:163], v[168:169], off offset:1536
	global_load_dwordx2 v[160:161], v[168:169], off offset:2048
	global_load_dwordx2 v[174:175], v[168:169], off
	global_load_dwordx2 v[150:151], v[154:155], off offset:2560
	global_load_dwordx2 v[152:153], v[154:155], off offset:3072
	s_nop 0
	global_load_dwordx2 v[154:155], v[154:155], off offset:3584
	s_nop 0
	global_load_dwordx2 v[156:157], v[156:157], off
	s_nop 0
	global_load_dwordx2 v[180:181], v[168:169], off offset:2560
	global_load_dwordx2 v[178:179], v[168:169], off offset:3072
	global_load_dwordx2 v[176:177], v[168:169], off offset:3584
	v_addc_co_u32_e32 v199, vcc, 0, v169, vcc
	global_load_dwordx2 v[158:159], v[188:189], off
	global_load_dwordx2 v[168:169], v[188:189], off offset:512
	global_load_dwordx2 v[170:171], v[188:189], off offset:1024
	global_load_dwordx2 v[172:173], v[188:189], off offset:1536
	global_load_dwordx2 v[196:197], v[198:199], off
	global_load_dwordx2 v[194:195], v[198:199], off offset:512
	global_load_dwordx2 v[192:193], v[198:199], off offset:1024
	global_load_dwordx2 v[190:191], v[198:199], off offset:1536
	global_load_dwordx2 v[182:183], v[188:189], off offset:2048
	global_load_dwordx2 v[184:185], v[188:189], off offset:2560
	global_load_dwordx2 v[186:187], v[188:189], off offset:3072
	s_nop 0
	global_load_dwordx2 v[188:189], v[188:189], off offset:3584
	s_nop 0
	global_load_dwordx2 v[204:205], v[198:199], off offset:2048
	global_load_dwordx2 v[202:203], v[198:199], off offset:2560
	global_load_dwordx2 v[200:201], v[198:199], off offset:3072
	s_nop 0
	global_load_dwordx2 v[198:199], v[198:199], off offset:3584

; #define GAS __attribute__((address_space(1)))
; __device__ __forceinline__ float bf_lo(unsigned w) { return __uint_as_float(w << 16); }
; __device__ __forceinline__ float bf_hi(unsigned w) { return __uint_as_float(w & 0xffff0000u); }
; __device__ __forceinline__ void pnl_finish(const Frame& F, int m, int lane, const u32x2 (&xw)[16], const u32x2 (&ov)[16], const f32x4 (&gv)[16]) {
;     GAS f32x4* yo = (GAS f32x4*)(F.out + (size_t)m * DM) + lane;
;     const float ss = wave_sum(F.RSQ[(size_t)m * 64 + lane], lane);
;     const float r = 1.0f / sqrtf(ss * (1.0f / DM) + RMS_EPS);
; #pragma unroll
;     for (int j = 0; j < 16; ++j) { const u32x2 x = xw[j], ow = ov[j]; const f32x4 g = gv[j];
;         f32x4 y; y.x = bf_lo(x.x) + bf_lo(ow.x) * r * g.x; y.y = bf_hi(x.x) + bf_hi(ow.x) * r * g.y; y.z = bf_lo(x.y) + bf_lo(ow.y) * r * g.z; y.w = bf_hi(x.y) + bf_hi(ow.y) * r * g.w;
;         yo[64 * j] = y; }
.Lpn_a_fin:
	s_ashr_i32 s89, s88, 31
	s_lshl_b64 s[8:9], s[88:89], 14
	v_lshl_add_u64 v[206:207], v[2:3], 0, s[8:9]
	s_mov_b32 s5, 0xf800000
	v_and_b32_e32 v219, 0xffff0000, v91
	v_lshl_add_u64 v[206:207], v[138:139], 4, v[206:207]
	v_lshlrev_b32_e32 v222, 16, v99
	v_and_b32_e32 v223, 0xffff0000, v99
	s_waitcnt lgkmcnt(0)
	ds_bpermute_b32 v208, v212, v0
	s_waitcnt lgkmcnt(0)
	v_add_f32_e32 v0, v0, v208
	ds_bpermute_b32 v208, v213, v0
	s_waitcnt lgkmcnt(0)
	v_add_f32_e32 v0, v0, v208
	ds_bpermute_b32 v208, v214, v0
	s_waitcnt lgkmcnt(0)
	v_add_f32_e32 v0, v0, v208
	ds_bpermute_b32 v208, v215, v0
	s_waitcnt lgkmcnt(0)
	v_add_f32_e32 v0, v0, v208
	ds_bpermute_b32 v208, v216, v0
	s_waitcnt lgkmcnt(0)
	v_add_f32_e32 v0, v0, v208
	ds_bpermute_b32 v208, v217, v0
	s_waitcnt lgkmcnt(0)
	v_add_f32_e32 v0, v0, v208
	v_mov_b32_e32 v208, 0x358637bd
	v_fmamk_f32 v0, v0, 0x39800000, v208
	v_cmp_gt_f32_e32 vcc, s5, v0
	v_mul_f32_e32 v208, 0x4f800000, v0
	s_movk_i32 s5, 0x2000
	v_cndmask_b32_e32 v0, v0, v208, vcc
	v_sqrt_f32_e32 v208, v0
	s_nop 0
	v_add_u32_e32 v209, -1, v208
	v_fma_f32 v210, -v209, v208, v0
	v_cmp_ge_f32_e64 s[36:37], 0, v210
	v_add_u32_e32 v210, 1, v208
	s_nop 0
	v_cndmask_b32_e64 v209, v208, v209, s[36:37]
	v_fma_f32 v208, -v210, v208, v0
	v_cmp_lt_f32_e64 s[36:37], 0, v208
	s_nop 1
	v_cndmask_b32_e64 v208, v209, v210, s[36:37]
	v_mul_f32_e32 v209, 0x37800000, v208
	v_cndmask_b32_e32 v208, v208, v209, vcc
	v_mov_b32_e32 v209, 0x260
	v_cmp_class_f32_e32 vcc, v0, v209
	s_nop 1
	v_cndmask_b32_e32 v0, v208, v0, vcc
	v_div_scale_f32 v208, s[8:9], v0, v0, 1.0
	v_rcp_f32_e32 v209, v208
	s_mov_b64 s[8:9], -1
	v_fma_f32 v210, -v208, v209, 1.0
	v_fmac_f32_e32 v209, v210, v209
	v_div_scale_f32 v210, vcc, 1.0, v0, 1.0
	v_mul_f32_e32 v211, v210, v209
	v_fma_f32 v218, -v208, v211, v210
	v_fmac_f32_e32 v211, v218, v209
	v_fma_f32 v208, -v208, v211, v210
	v_div_fmas_f32 v208, v208, v209, v211
	v_div_fixup_f32 v0, v208, v0, 1.0
	v_lshlrev_b32_e32 v210, 16, v90
	v_and_b32_e32 v211, 0xffff0000, v90
	v_lshlrev_b32_e32 v208, 16, v106
	v_and_b32_e32 v209, 0xffff0000, v106
	v_pk_mul_f32 v[210:211], v[0:1], v[210:211] op_sel_hi:[0,1]
	v_lshlrev_b32_e32 v218, 16, v91
	v_pk_fma_f32 v[208:209], v[66:67], v[210:211], v[208:209]
	v_lshlrev_b32_e32 v210, 16, v107
	v_and_b32_e32 v211, 0xffff0000, v107
	v_pk_mul_f32 v[218:219], v[0:1], v[218:219] op_sel_hi:[0,1]
	v_pk_fma_f32 v[210:211], v[68:69], v[218:219], v[210:211]
	global_store_dwordx4 v[206:207], v[208:211], off
	v_lshlrev_b32_e32 v218, 16, v83
	v_and_b32_e32 v219, 0xffff0000, v83
	v_lshlrev_b32_e32 v210, 16, v82
	v_and_b32_e32 v211, 0xffff0000, v82
	v_lshlrev_b32_e32 v208, 16, v74
	v_and_b32_e32 v209, 0xffff0000, v74
	v_pk_mul_f32 v[210:211], v[0:1], v[210:211] op_sel_hi:[0,1]
	v_pk_fma_f32 v[208:209], v[62:63], v[210:211], v[208:209]
	v_lshlrev_b32_e32 v210, 16, v75
	v_and_b32_e32 v211, 0xffff0000, v75
	v_pk_mul_f32 v[218:219], v[0:1], v[218:219] op_sel_hi:[0,1]
	v_pk_fma_f32 v[210:211], v[64:65], v[218:219], v[210:211]
	global_store_dwordx4 v[206:207], v[208:211], off offset:1024
	v_lshlrev_b32_e32 v218, 16, v85
	v_and_b32_e32 v219, 0xffff0000, v85
	v_lshlrev_b32_e32 v210, 16, v84
	v_and_b32_e32 v211, 0xffff0000, v84
	v_lshlrev_b32_e32 v208, 16, v76
	v_and_b32_e32 v209, 0xffff0000, v76
	v_pk_mul_f32 v[210:211], v[0:1], v[210:211] op_sel_hi:[0,1]
	v_pk_fma_f32 v[208:209], v[58:59], v[210:211], v[208:209]
	v_lshlrev_b32_e32 v210, 16, v77
	v_and_b32_e32 v211, 0xffff0000, v77
	v_pk_mul_f32 v[218:219], v[0:1], v[218:219] op_sel_hi:[0,1]
	v_pk_fma_f32 v[210:211], v[60:61], v[218:219], v[210:211]
	global_store_dwordx4 v[206:207], v[208:211], off offset:2048
	v_lshlrev_b32_e32 v218, 16, v87
	v_and_b32_e32 v219, 0xffff0000, v87
	v_lshlrev_b32_e32 v210, 16, v86
	v_and_b32_e32 v211, 0xffff0000, v86
	v_lshlrev_b32_e32 v208, 16, v78
	v_and_b32_e32 v209, 0xffff0000, v78
	v_pk_mul_f32 v[210:211], v[0:1], v[210:211] op_sel_hi:[0,1]
	v_pk_fma_f32 v[208:209], v[54:55], v[210:211], v[208:209]
	v_lshlrev_b32_e32 v210, 16, v79
	v_and_b32_e32 v211, 0xffff0000, v79
	v_pk_mul_f32 v[218:219], v[0:1], v[218:219] op_sel_hi:[0,1]
	v_pk_fma_f32 v[210:211], v[56:57], v[218:219], v[210:211]
	global_store_dwordx4 v[206:207], v[208:211], off offset:3072
	v_pk_mul_f32 v[222:223], v[0:1], v[222:223] op_sel_hi:[0,1]
	v_readfirstlane_b32 s88, v0
	v_lshlrev_b32_e32 v210, 16, v88
	v_and_b32_e32 v211, 0xffff0000, v88
	v_lshlrev_b32_e32 v208, 16, v80
	v_and_b32_e32 v209, 0xffff0000, v80
	v_pk_mul_f32 v[210:211], v[0:1], v[210:211] op_sel_hi:[0,1]
	v_pk_fma_f32 v[218:219], v[50:51], v[210:211], v[208:209]
	v_lshlrev_b32_e32 v210, 16, v89
	v_and_b32_e32 v211, 0xffff0000, v89
	v_lshlrev_b32_e32 v208, 16, v81
	v_and_b32_e32 v209, 0xffff0000, v81
	v_pk_mul_f32 v[210:211], v[0:1], v[210:211] op_sel_hi:[0,1]
	v_pk_fma_f32 v[220:221], v[52:53], v[210:211], v[208:209]
	v_add_co_u32_e32 v210, vcc, s35, v206
	s_nop 1
	v_addc_co_u32_e32 v211, vcc, 0, v207, vcc
	v_add_co_u32_e32 v208, vcc, s5, v206
	s_movk_i32 s5, 0x3000
	s_nop 0
	v_addc_co_u32_e32 v209, vcc, 0, v207, vcc
	global_store_dwordx4 v[208:209], v[218:221], off offset:-4096
	s_nop 1
	v_lshlrev_b32_e32 v220, 16, v98
	v_and_b32_e32 v221, 0xffff0000, v98
	v_lshlrev_b32_e32 v218, 16, v92
	v_and_b32_e32 v219, 0xffff0000, v92
	v_pk_mul_f32 v[220:221], v[0:1], v[220:221] op_sel_hi:[0,1]
	v_pk_fma_f32 v[218:219], v[46:47], v[220:221], v[218:219]
	v_lshlrev_b32_e32 v220, 16, v93
	v_and_b32_e32 v221, 0xffff0000, v93
	v_pk_fma_f32 v[220:221], v[48:49], v[222:223], v[220:221]
	global_store_dwordx4 v[210:211], v[218:221], off offset:1024
	v_lshlrev_b32_e32 v222, 16, v101
	v_and_b32_e32 v223, 0xffff0000, v101
; __device__ __forceinline__ float bf_lo(unsigned w) { return __uint_as_float(w << 16); }
; __device__ __forceinline__ float bf_hi(unsigned w) { return __uint_as_float(w & 0xffff0000u); }
; __device__ __forceinline__ void pnl_finish(const Frame& F, int m, int lane, const u32x2 (&xw)[16], const u32x2 (&ov)[16], const f32x4 (&gv)[16]) {
;     ...
;     for (int j = 0; j < 16; ++j) { const u32x2 x = xw[j], ow = ov[j]; const f32x4 g = gv[j];
;         f32x4 y; y.x = bf_lo(x.x) + bf_lo(ow.x) * r * g.x; y.y = bf_hi(x.x) + bf_hi(ow.x) * r * g.y; y.z = bf_lo(x.y) + bf_lo(ow.y) * r * g.z; y.w = bf_hi(x.y) + bf_hi(ow.y) * r * g.w;
;         yo[64 * j] = y; }
	v_lshlrev_b32_e32 v220, 16, v100
	v_and_b32_e32 v221, 0xffff0000, v100
	v_lshlrev_b32_e32 v218, 16, v94
	v_and_b32_e32 v219, 0xffff0000, v94
	v_pk_mul_f32 v[220:221], v[0:1], v[220:221] op_sel_hi:[0,1]
	v_pk_fma_f32 v[218:219], v[42:43], v[220:221], v[218:219]
	v_lshlrev_b32_e32 v220, 16, v95
	v_and_b32_e32 v221, 0xffff0000, v95
	v_pk_mul_f32 v[222:223], v[0:1], v[222:223] op_sel_hi:[0,1]
	v_pk_fma_f32 v[220:221], v[44:45], v[222:223], v[220:221]
	global_store_dwordx4 v[210:211], v[218:221], off offset:2048
	v_lshlrev_b32_e32 v222, 16, v103
	v_and_b32_e32 v223, 0xffff0000, v103
	v_lshlrev_b32_e32 v220, 16, v102
	v_and_b32_e32 v221, 0xffff0000, v102
	v_lshlrev_b32_e32 v218, 16, v96
	v_and_b32_e32 v219, 0xffff0000, v96
	v_pk_mul_f32 v[220:221], v[0:1], v[220:221] op_sel_hi:[0,1]
	v_pk_fma_f32 v[218:219], v[38:39], v[220:221], v[218:219]
	v_lshlrev_b32_e32 v220, 16, v97
	v_and_b32_e32 v221, 0xffff0000, v97
	v_pk_mul_f32 v[222:223], v[0:1], v[222:223] op_sel_hi:[0,1]
	v_pk_fma_f32 v[220:221], v[40:41], v[222:223], v[220:221]
	global_store_dwordx4 v[210:211], v[218:221], off offset:3072
	v_lshlrev_b32_e32 v210, 16, v104
	v_and_b32_e32 v211, 0xffff0000, v104
	v_lshlrev_b32_e32 v218, 16, v110
	v_and_b32_e32 v219, 0xffff0000, v110
	v_pk_mul_f32 v[218:219], v[0:1], v[218:219] op_sel_hi:[0,1]
	v_lshlrev_b32_e32 v220, 16, v111
	v_and_b32_e32 v221, 0xffff0000, v111
	v_pk_fma_f32 v[218:219], v[34:35], v[218:219], v[210:211]
	v_lshlrev_b32_e32 v210, 16, v105
	v_and_b32_e32 v211, 0xffff0000, v105
	v_pk_mul_f32 v[220:221], v[0:1], v[220:221] op_sel_hi:[0,1]
	v_pk_fma_f32 v[220:221], v[36:37], v[220:221], v[210:211]
	global_store_dwordx4 v[208:209], v[218:221], off
	v_lshlrev_b32_e32 v210, 16, v108
	v_and_b32_e32 v211, 0xffff0000, v108
	v_lshlrev_b32_e32 v218, 16, v116
	v_and_b32_e32 v219, 0xffff0000, v116
	v_pk_mul_f32 v[218:219], v[0:1], v[218:219] op_sel_hi:[0,1]
	v_lshlrev_b32_e32 v220, 16, v117
	v_and_b32_e32 v221, 0xffff0000, v117
	v_pk_fma_f32 v[218:219], v[30:31], v[218:219], v[210:211]
	v_lshlrev_b32_e32 v210, 16, v109
	v_and_b32_e32 v211, 0xffff0000, v109
	v_pk_mul_f32 v[220:221], v[0:1], v[220:221] op_sel_hi:[0,1]
	v_pk_fma_f32 v[220:221], v[32:33], v[220:221], v[210:211]
	global_store_dwordx4 v[208:209], v[218:221], off offset:1024
	v_lshlrev_b32_e32 v210, 16, v112
	v_and_b32_e32 v211, 0xffff0000, v112
	v_lshlrev_b32_e32 v218, 16, v118
	v_and_b32_e32 v219, 0xffff0000, v118
	v_pk_mul_f32 v[218:219], v[0:1], v[218:219] op_sel_hi:[0,1]
	v_lshlrev_b32_e32 v220, 16, v119
	v_and_b32_e32 v221, 0xffff0000, v119
	v_pk_fma_f32 v[218:219], v[26:27], v[218:219], v[210:211]
	v_lshlrev_b32_e32 v210, 16, v113
	v_and_b32_e32 v211, 0xffff0000, v113
	v_pk_mul_f32 v[220:221], v[0:1], v[220:221] op_sel_hi:[0,1]
	v_pk_fma_f32 v[220:221], v[28:29], v[220:221], v[210:211]
	global_store_dwordx4 v[208:209], v[218:221], off offset:2048
	v_lshlrev_b32_e32 v210, 16, v114
	v_and_b32_e32 v211, 0xffff0000, v114
	v_lshlrev_b32_e32 v218, 16, v120
	v_and_b32_e32 v219, 0xffff0000, v120
	v_pk_mul_f32 v[218:219], v[0:1], v[218:219] op_sel_hi:[0,1]
	v_lshlrev_b32_e32 v220, 16, v121
	v_and_b32_e32 v221, 0xffff0000, v121
	v_pk_fma_f32 v[218:219], v[22:23], v[218:219], v[210:211]
	v_lshlrev_b32_e32 v210, 16, v115
	v_and_b32_e32 v211, 0xffff0000, v115
	v_pk_mul_f32 v[220:221], v[0:1], v[220:221] op_sel_hi:[0,1]
	v_pk_fma_f32 v[220:221], v[24:25], v[220:221], v[210:211]
	v_lshlrev_b32_e32 v210, 16, v126
	v_and_b32_e32 v211, 0xffff0000, v126
	global_store_dwordx4 v[208:209], v[218:221], off offset:3072
	v_lshlrev_b32_e32 v208, 16, v122
	v_and_b32_e32 v209, 0xffff0000, v122
	v_pk_mul_f32 v[210:211], v[0:1], v[210:211] op_sel_hi:[0,1]
	v_lshlrev_b32_e32 v218, 16, v127
	v_and_b32_e32 v219, 0xffff0000, v127
	v_pk_fma_f32 v[208:209], v[18:19], v[210:211], v[208:209]
	v_lshlrev_b32_e32 v210, 16, v123
	v_and_b32_e32 v211, 0xffff0000, v123
	v_pk_mul_f32 v[218:219], v[0:1], v[218:219] op_sel_hi:[0,1]
	v_pk_fma_f32 v[210:211], v[20:21], v[218:219], v[210:211]
	v_add_co_u32_e32 v218, vcc, s5, v206
	v_lshlrev_b32_e32 v206, 16, v124
	s_nop 0
	v_addc_co_u32_e32 v219, vcc, 0, v207, vcc
	global_store_dwordx4 v[218:219], v[208:211], off
	v_and_b32_e32 v207, 0xffff0000, v124
	s_andn2_b64 vcc, exec, s[10:11]
	v_lshlrev_b32_e32 v208, 16, v132
	v_and_b32_e32 v209, 0xffff0000, v132
	v_pk_mul_f32 v[208:209], v[0:1], v[208:209] op_sel_hi:[0,1]
	v_lshlrev_b32_e32 v210, 16, v133
	v_and_b32_e32 v211, 0xffff0000, v133
	v_pk_fma_f32 v[206:207], v[14:15], v[208:209], v[206:207]
	v_lshlrev_b32_e32 v208, 16, v125
	v_and_b32_e32 v209, 0xffff0000, v125
	v_pk_mul_f32 v[210:211], v[0:1], v[210:211] op_sel_hi:[0,1]
	v_pk_fma_f32 v[208:209], v[16:17], v[210:211], v[208:209]
	global_store_dwordx4 v[218:219], v[206:209], off offset:1024
	v_lshlrev_b32_e32 v210, 16, v135
	v_and_b32_e32 v211, 0xffff0000, v135
	v_lshlrev_b32_e32 v208, 16, v134
	v_and_b32_e32 v209, 0xffff0000, v134
	v_lshlrev_b32_e32 v206, 16, v128
	v_and_b32_e32 v207, 0xffff0000, v128
	v_pk_mul_f32 v[208:209], v[0:1], v[208:209] op_sel_hi:[0,1]
	v_pk_fma_f32 v[206:207], v[10:11], v[208:209], v[206:207]
	v_lshlrev_b32_e32 v208, 16, v129
	v_and_b32_e32 v209, 0xffff0000, v129
	v_pk_mul_f32 v[210:211], v[0:1], v[210:211] op_sel_hi:[0,1]
	v_pk_fma_f32 v[208:209], v[12:13], v[210:211], v[208:209]
	global_store_dwordx4 v[218:219], v[206:209], off offset:2048
	v_lshlrev_b32_e32 v210, 16, v137
	v_and_b32_e32 v211, 0xffff0000, v137
	v_lshlrev_b32_e32 v208, 16, v136
	v_and_b32_e32 v209, 0xffff0000, v136
	v_lshlrev_b32_e32 v206, 16, v130
	v_and_b32_e32 v207, 0xffff0000, v130
	v_pk_mul_f32 v[208:209], v[0:1], v[208:209] op_sel_hi:[0,1]
	v_pk_fma_f32 v[206:207], v[6:7], v[208:209], v[206:207]
	v_lshlrev_b32_e32 v208, 16, v131
	v_and_b32_e32 v209, 0xffff0000, v131
	v_pk_mul_f32 v[210:211], v[0:1], v[210:211] op_sel_hi:[0,1]
	v_pk_fma_f32 v[208:209], v[8:9], v[210:211], v[208:209]
	global_store_dwordx4 v[218:219], v[206:209], off offset:3072
	s_cbranch_vccnz .LBB0_1022
; #define GAS __attribute__((address_space(1)))
; __device__ __forceinline__ void pnl_load(const Frame& F, int m, int lane, u32x2 (&xw)[16], u32x2 (&ov)[16]) {
;     const GAS u32x2* x1row = (const GAS u32x2*)(F.P + (size_t)m * INW + 18432) + lane; const GAS u32x2* orow = (const GAS u32x2*)(F.X + (size_t)m * DM) + lane;
; #pragma unroll
;     for (int j = 0; j < 16; ++j) { xw[j] = x1row[64 * j]; ov[j] = orow[64 * j]; }
; }
; __device__ __forceinline__ void pnl_finish(const Frame& F, int m, int lane, const u32x2 (&xw)[16], const u32x2 (&ov)[16], const f32x4 (&gv)[16]) {
;     GAS f32x4* yo = (GAS f32x4*)(F.out + (size_t)m * DM) + lane;
;     const float ss = wave_sum(F.RSQ[(size_t)m * 64 + lane], lane);
; __device__ __forceinline__ void post_norm_phase(Frame& F, int l) {
;     ...
;             hn = m + NGW < T; if (hn) pnl_load(F, m + NGW, lane, xa, oa);
;             pnl_finish(F, m, lane, xb, ob, gv); if (!hn) break; m += NGW; }
	s_ashr_i32 s5, s4, 31
	s_lshl_b64 s[12:13], s[4:5], 8
	v_lshl_add_u64 v[208:209], v[4:5], 0, s[12:13]
	global_load_dword v0, v[208:209], off
	s_add_i32 s10, s4, s96
	s_cmpk_gt_i32 s10, 0x5fff
	s_cselect_b64 s[8:9], -1, 0
	s_and_b64 vcc, exec, s[8:9]
	s_mov_b32 s88, s4
	s_cbranch_vccnz .Lpn_b_last
	v_mad_i64_i32 v[74:75], s[12:13], s10, v224, v[140:141]
	v_lshl_add_u64 v[104:105], v[74:75], 0, v[72:73]
	s_ashr_i32 s11, s10, 31
	s_mov_b64 s[12:13], 0x9000
	v_add_co_u32_e32 v98, vcc, 0x9000, v104
	v_lshl_add_u64 v[96:97], v[104:105], 0, s[12:13]
	s_lshl_b64 s[12:13], s[10:11], 13
	v_addc_co_u32_e32 v99, vcc, 0, v105, vcc
	s_mov_b32 s5, 0xa000
	v_lshl_add_u64 v[74:75], v[70:71], 0, s[12:13]
	v_add_co_u32_e32 v126, vcc, s5, v104
	v_lshl_add_u64 v[108:109], v[74:75], 0, v[72:73]
	s_nop 0
	v_addc_co_u32_e32 v127, vcc, 0, v105, vcc
	v_add_co_u32_e32 v136, vcc, s35, v108
	global_load_dwordx2 v[74:75], v[96:97], off offset:512
	global_load_dwordx2 v[76:77], v[96:97], off offset:1024
	global_load_dwordx2 v[78:79], v[96:97], off offset:1536
	global_load_dwordx2 v[80:81], v[96:97], off offset:2048
	global_load_dwordx2 v[82:83], v[108:109], off offset:512
	global_load_dwordx2 v[84:85], v[108:109], off offset:1024
	global_load_dwordx2 v[86:87], v[108:109], off offset:1536
	global_load_dwordx2 v[88:89], v[108:109], off offset:2048
	global_load_dwordx2 v[90:91], v[108:109], off
	global_load_dwordx2 v[92:93], v[96:97], off offset:2560
	global_load_dwordx2 v[94:95], v[96:97], off offset:3072
	s_nop 0
	global_load_dwordx2 v[96:97], v[96:97], off offset:3584
	s_nop 0
	global_load_dwordx2 v[106:107], v[98:99], off
	s_nop 0
	global_load_dwordx2 v[98:99], v[108:109], off offset:2560
	global_load_dwordx2 v[100:101], v[108:109], off offset:3072
	global_load_dwordx2 v[102:103], v[108:109], off offset:3584
	v_addc_co_u32_e32 v137, vcc, 0, v109, vcc
	global_load_dwordx2 v[104:105], v[126:127], off
	global_load_dwordx2 v[108:109], v[126:127], off offset:512
	global_load_dwordx2 v[112:113], v[126:127], off offset:1024
	global_load_dwordx2 v[114:115], v[126:127], off offset:1536
	global_load_dwordx2 v[110:111], v[136:137], off
	global_load_dwordx2 v[116:117], v[136:137], off offset:512
	global_load_dwordx2 v[118:119], v[136:137], off offset:1024
	global_load_dwordx2 v[120:121], v[136:137], off offset:1536
	global_load_dwordx2 v[122:123], v[126:127], off offset:2048
	global_load_dwordx2 v[124:125], v[126:127], off offset:2560
	global_load_dwordx2 v[128:129], v[126:127], off offset:3072
	global_load_dwordx2 v[130:131], v[126:127], off offset:3584
	s_nop 0
	global_load_dwordx2 v[126:127], v[136:137], off offset:2048
	global_load_dwordx2 v[132:133], v[136:137], off offset:2560
	global_load_dwordx2 v[134:135], v[136:137], off offset:3072
	s_nop 0
	global_load_dwordx2 v[136:137], v[136:137], off offset:3584
	s_mov_b32 s88, s10
	s_branch .LBB0_1021
